# phase-4 K loop: LDS-DMA loads in saddr form (SGPR base + VGPR offset + immediate), no per-load 64-bit VALU adds
# speedup vs baseline: 1.0085x; 1.0085x over previous
.LBB0_1102:
	v_mov_b32_e32 v137, 0
	s_and_b64 vcc, exec, s[4:5]
	v_mov_b32_e32 v136, v137
	v_mov_b32_e32 v135, v137
	v_mov_b32_e32 v134, v137
	v_mov_b32_e32 v121, v137
	v_mov_b32_e32 v120, v137
	v_mov_b32_e32 v119, v137
	v_mov_b32_e32 v118, v137
	v_mov_b32_e32 v113, v137
	v_mov_b32_e32 v112, v137
	v_mov_b32_e32 v111, v137
	v_mov_b32_e32 v110, v137
	v_mov_b32_e32 v105, v137
	v_mov_b32_e32 v104, v137
	v_mov_b32_e32 v103, v137
	v_mov_b32_e32 v102, v137
	v_mov_b32_e32 v97, v137
	v_mov_b32_e32 v96, v137
	v_mov_b32_e32 v95, v137
	v_mov_b32_e32 v94, v137
	v_mov_b32_e32 v89, v137
	v_mov_b32_e32 v88, v137
	v_mov_b32_e32 v87, v137
	v_mov_b32_e32 v86, v137
	v_mov_b32_e32 v81, v137
	v_mov_b32_e32 v80, v137
	v_mov_b32_e32 v79, v137
	v_mov_b32_e32 v78, v137
	v_mov_b32_e32 v73, v137
	v_mov_b32_e32 v72, v137
	v_mov_b32_e32 v71, v137
	v_mov_b32_e32 v70, v137
	v_mov_b32_e32 v133, v137
	v_mov_b32_e32 v132, v137
	v_mov_b32_e32 v131, v137
	v_mov_b32_e32 v130, v137
	v_mov_b32_e32 v117, v137
	v_mov_b32_e32 v116, v137
	v_mov_b32_e32 v115, v137
	v_mov_b32_e32 v114, v137
	v_mov_b32_e32 v109, v137
	v_mov_b32_e32 v108, v137
	v_mov_b32_e32 v107, v137
	v_mov_b32_e32 v106, v137
	v_mov_b32_e32 v101, v137
	v_mov_b32_e32 v100, v137
	v_mov_b32_e32 v99, v137
	v_mov_b32_e32 v98, v137
	v_mov_b32_e32 v93, v137
	v_mov_b32_e32 v92, v137
	v_mov_b32_e32 v91, v137
	v_mov_b32_e32 v90, v137
	v_mov_b32_e32 v85, v137
	v_mov_b32_e32 v84, v137
	v_mov_b32_e32 v83, v137
	v_mov_b32_e32 v82, v137
	v_mov_b32_e32 v77, v137
	v_mov_b32_e32 v76, v137
	v_mov_b32_e32 v75, v137
	v_mov_b32_e32 v74, v137
	v_mov_b32_e32 v69, v137
	v_mov_b32_e32 v68, v137
	v_mov_b32_e32 v67, v137
	v_mov_b32_e32 v66, v137
	v_mov_b32_e32 v65, v137
	v_mov_b32_e32 v64, v137
	v_mov_b32_e32 v63, v137
	v_mov_b32_e32 v62, v137
	v_mov_b32_e32 v57, v137
	v_mov_b32_e32 v56, v137
	v_mov_b32_e32 v55, v137
	v_mov_b32_e32 v54, v137
	v_mov_b32_e32 v49, v137
	v_mov_b32_e32 v48, v137
	v_mov_b32_e32 v47, v137
	v_mov_b32_e32 v46, v137
	v_mov_b32_e32 v41, v137
	v_mov_b32_e32 v40, v137
	v_mov_b32_e32 v39, v137
	v_mov_b32_e32 v38, v137
	v_mov_b32_e32 v33, v137
	v_mov_b32_e32 v32, v137
	v_mov_b32_e32 v31, v137
	v_mov_b32_e32 v30, v137
	v_mov_b32_e32 v25, v137
	v_mov_b32_e32 v24, v137
	v_mov_b32_e32 v23, v137
	v_mov_b32_e32 v22, v137
	v_mov_b32_e32 v17, v137
	v_mov_b32_e32 v16, v137
	v_mov_b32_e32 v15, v137
	v_mov_b32_e32 v14, v137
	v_mov_b32_e32 v9, v137
	v_mov_b32_e32 v8, v137
	v_mov_b32_e32 v7, v137
	v_mov_b32_e32 v6, v137
	v_mov_b32_e32 v61, v137
	v_mov_b32_e32 v60, v137
	v_mov_b32_e32 v59, v137
	v_mov_b32_e32 v58, v137
	v_mov_b32_e32 v53, v137
	v_mov_b32_e32 v52, v137
	v_mov_b32_e32 v51, v137
	v_mov_b32_e32 v50, v137
	v_mov_b32_e32 v45, v137
	v_mov_b32_e32 v44, v137
	v_mov_b32_e32 v43, v137
	v_mov_b32_e32 v42, v137
	v_mov_b32_e32 v37, v137
	v_mov_b32_e32 v36, v137
	v_mov_b32_e32 v35, v137
	v_mov_b32_e32 v34, v137
	v_mov_b32_e32 v29, v137
	v_mov_b32_e32 v28, v137
	v_mov_b32_e32 v27, v137
	v_mov_b32_e32 v26, v137
	v_mov_b32_e32 v21, v137
	v_mov_b32_e32 v20, v137
	v_mov_b32_e32 v19, v137
	v_mov_b32_e32 v18, v137
	v_mov_b32_e32 v13, v137
	v_mov_b32_e32 v12, v137
	v_mov_b32_e32 v11, v137
	v_mov_b32_e32 v10, v137
	v_mov_b32_e32 v5, v137
	v_mov_b32_e32 v4, v137
	v_mov_b32_e32 v3, v137
	v_mov_b32_e32 v2, v137
	s_cbranch_vccnz .LBB0_1095
	s_add_u32 s0, s28, 0x80
	s_addc_u32 s1, s29, 0
	s_add_u32 s28, s26, 0x100
	v_mov_b32_e32 v2, 0
	s_addc_u32 s29, s27, 0
	s_mov_b32 s2, 0
	v_mov_b32_e32 v3, v2
	v_mov_b32_e32 v4, v2
	v_mov_b32_e32 v5, v2
	v_mov_b32_e32 v10, v2
	v_mov_b32_e32 v11, v2
	v_mov_b32_e32 v12, v2
	v_mov_b32_e32 v13, v2
	v_mov_b32_e32 v18, v2
	v_mov_b32_e32 v19, v2
	v_mov_b32_e32 v20, v2
	v_mov_b32_e32 v21, v2
	v_mov_b32_e32 v26, v2
	v_mov_b32_e32 v27, v2
	v_mov_b32_e32 v28, v2
	v_mov_b32_e32 v29, v2
	v_mov_b32_e32 v34, v2
	v_mov_b32_e32 v35, v2
	v_mov_b32_e32 v36, v2
	v_mov_b32_e32 v37, v2
	v_mov_b32_e32 v42, v2
	v_mov_b32_e32 v43, v2
	v_mov_b32_e32 v44, v2
	v_mov_b32_e32 v45, v2
	v_mov_b32_e32 v50, v2
	v_mov_b32_e32 v51, v2
	v_mov_b32_e32 v52, v2
	v_mov_b32_e32 v53, v2
	v_mov_b32_e32 v58, v2
	v_mov_b32_e32 v59, v2
	v_mov_b32_e32 v60, v2
	v_mov_b32_e32 v61, v2
	v_mov_b32_e32 v6, v2
	v_mov_b32_e32 v7, v2
	v_mov_b32_e32 v8, v2
	v_mov_b32_e32 v9, v2
	v_mov_b32_e32 v14, v2
	v_mov_b32_e32 v15, v2
	v_mov_b32_e32 v16, v2
	v_mov_b32_e32 v17, v2
	v_mov_b32_e32 v22, v2
	v_mov_b32_e32 v23, v2
	v_mov_b32_e32 v24, v2
	v_mov_b32_e32 v25, v2
	v_mov_b32_e32 v30, v2
	v_mov_b32_e32 v31, v2
	v_mov_b32_e32 v32, v2
	v_mov_b32_e32 v33, v2
	v_mov_b32_e32 v38, v2
	v_mov_b32_e32 v39, v2
	v_mov_b32_e32 v40, v2
	v_mov_b32_e32 v41, v2
	v_mov_b32_e32 v46, v2
	v_mov_b32_e32 v47, v2
	v_mov_b32_e32 v48, v2
	v_mov_b32_e32 v49, v2
	v_mov_b32_e32 v54, v2
	v_mov_b32_e32 v55, v2
	v_mov_b32_e32 v56, v2
	v_mov_b32_e32 v57, v2
	v_mov_b32_e32 v62, v2
	v_mov_b32_e32 v63, v2
	v_mov_b32_e32 v64, v2
	v_mov_b32_e32 v65, v2
	v_mov_b32_e32 v66, v2
	v_mov_b32_e32 v67, v2
	v_mov_b32_e32 v68, v2
	v_mov_b32_e32 v69, v2
	v_mov_b32_e32 v74, v2
	v_mov_b32_e32 v75, v2
	v_mov_b32_e32 v76, v2
	v_mov_b32_e32 v77, v2
	v_mov_b32_e32 v82, v2
	v_mov_b32_e32 v83, v2
	v_mov_b32_e32 v84, v2
	v_mov_b32_e32 v85, v2
	v_mov_b32_e32 v90, v2
	v_mov_b32_e32 v91, v2
	v_mov_b32_e32 v92, v2
	v_mov_b32_e32 v93, v2
	v_mov_b32_e32 v98, v2
	v_mov_b32_e32 v99, v2
	v_mov_b32_e32 v100, v2
	v_mov_b32_e32 v101, v2
	v_mov_b32_e32 v106, v2
	v_mov_b32_e32 v107, v2
	v_mov_b32_e32 v108, v2
	v_mov_b32_e32 v109, v2
	v_mov_b32_e32 v114, v2
	v_mov_b32_e32 v115, v2
	v_mov_b32_e32 v116, v2
	v_mov_b32_e32 v117, v2
	v_mov_b32_e32 v130, v2
	v_mov_b32_e32 v131, v2
	v_mov_b32_e32 v132, v2
	v_mov_b32_e32 v133, v2
	v_mov_b32_e32 v70, v2
	v_mov_b32_e32 v71, v2
	v_mov_b32_e32 v72, v2
	v_mov_b32_e32 v73, v2
	v_mov_b32_e32 v78, v2
	v_mov_b32_e32 v79, v2
	v_mov_b32_e32 v80, v2
	v_mov_b32_e32 v81, v2
	v_mov_b32_e32 v86, v2
	v_mov_b32_e32 v87, v2
	v_mov_b32_e32 v88, v2
	v_mov_b32_e32 v89, v2
	v_mov_b32_e32 v94, v2
	v_mov_b32_e32 v95, v2
	v_mov_b32_e32 v96, v2
	v_mov_b32_e32 v97, v2
	v_mov_b32_e32 v102, v2
	v_mov_b32_e32 v103, v2
	v_mov_b32_e32 v104, v2
	v_mov_b32_e32 v105, v2
	v_mov_b32_e32 v110, v2
	v_mov_b32_e32 v111, v2
	v_mov_b32_e32 v112, v2
	v_mov_b32_e32 v113, v2
	v_mov_b32_e32 v118, v2
	v_mov_b32_e32 v119, v2
	v_mov_b32_e32 v120, v2
	v_mov_b32_e32 v121, v2
	v_mov_b32_e32 v134, v2
	v_mov_b32_e32 v135, v2
	v_mov_b32_e32 v136, v2
	v_mov_b32_e32 v137, v2
	v_add_u32_e32 v241, s22, v164
	v_add_u32_e32 v240, s22, v166
.LBB0_1104:
	ds_read_b128 v[122:125], v185
	ds_read_b128 v[126:129], v186
	ds_read_b128 v[138:141], v187
	ds_read_b128 v[142:145], v188
	s_add_i32 s36, s2, 2
	s_add_u32 s26, s0, 0x80
	s_addc_u32 s3, s1, 0
	s_cmp_eq_u32 s58, s2
	s_cselect_b32 s2, s8, s26
	s_cselect_b32 s3, s9, s3
	s_cselect_b32 s27, s55, s29
	s_cselect_b32 s26, s54, s28
	s_mov_b32 m0, s61
	ds_read_b128 v[146:149], v183
	ds_read_b128 v[150:153], v183 offset:1024
	ds_read_b128 v[154:157], v183 offset:2048
	ds_read_b128 v[158:161], v183 offset:3072
	ds_read_b128 v[176:179], v183 offset:4096
	ds_read_b128 v[202:205], v183 offset:5120
	ds_read_b128 v[206:209], v183 offset:6144
	ds_read_b128 v[210:213], v183 offset:7168
	global_load_lds_dwordx4 v168, s[0:1]
	s_mov_b32 m0, s62
	s_nop 0
	global_load_lds_dwordx4 v170, s[0:1]
	s_waitcnt lgkmcnt(8)
	s_barrier
	s_waitcnt lgkmcnt(0)
	s_waitcnt lgkmcnt(0)
	v_mfma_f32_16x16x32_bf16 v[134:137], v[122:125], v[146:149], v[134:137]
	v_mfma_f32_16x16x32_bf16 v[118:121], v[138:141], v[146:149], v[118:121]
	v_mfma_f32_16x16x32_bf16 v[110:113], v[122:125], v[154:157], v[110:113]
	v_mfma_f32_16x16x32_bf16 v[102:105], v[138:141], v[154:157], v[102:105]
	v_mfma_f32_16x16x32_bf16 v[94:97], v[122:125], v[176:179], v[94:97]
	v_mfma_f32_16x16x32_bf16 v[86:89], v[138:141], v[176:179], v[86:89]
	v_mfma_f32_16x16x32_bf16 v[78:81], v[122:125], v[206:209], v[78:81]
	v_mfma_f32_16x16x32_bf16 v[70:73], v[138:141], v[206:209], v[70:73]
	v_mfma_f32_16x16x32_bf16 v[134:137], v[126:129], v[150:153], v[134:137]
	v_mfma_f32_16x16x32_bf16 v[118:121], v[142:145], v[150:153], v[118:121]
	v_mfma_f32_16x16x32_bf16 v[110:113], v[126:129], v[158:161], v[110:113]
	v_mfma_f32_16x16x32_bf16 v[102:105], v[142:145], v[158:161], v[102:105]
	v_mfma_f32_16x16x32_bf16 v[94:97], v[126:129], v[202:205], v[94:97]
	v_mfma_f32_16x16x32_bf16 v[86:89], v[142:145], v[202:205], v[86:89]
	v_mfma_f32_16x16x32_bf16 v[78:81], v[126:129], v[210:213], v[78:81]
	v_mfma_f32_16x16x32_bf16 v[70:73], v[142:145], v[210:213], v[70:73]
	s_barrier
	s_mov_b32 m0, s35
	ds_read_b128 v[214:217], v189
	ds_read_b128 v[218:221], v190
	ds_read_b128 v[222:225], v191
	ds_read_b128 v[226:229], v192
	global_load_lds_dwordx4 v166, s[26:27]
	s_mov_b32 m0, s38
	s_nop 0
	global_load_lds_dwordx4 v164, s[26:27]
	s_barrier
	s_waitcnt lgkmcnt(0)
	s_waitcnt lgkmcnt(0)
	v_mfma_f32_16x16x32_bf16 v[130:133], v[214:217], v[146:149], v[130:133]
	v_mfma_f32_16x16x32_bf16 v[114:117], v[222:225], v[146:149], v[114:117]
	v_mfma_f32_16x16x32_bf16 v[106:109], v[214:217], v[154:157], v[106:109]
	v_mfma_f32_16x16x32_bf16 v[98:101], v[222:225], v[154:157], v[98:101]
	v_mfma_f32_16x16x32_bf16 v[90:93], v[214:217], v[176:179], v[90:93]
	v_mfma_f32_16x16x32_bf16 v[82:85], v[222:225], v[176:179], v[82:85]
	v_mfma_f32_16x16x32_bf16 v[74:77], v[214:217], v[206:209], v[74:77]
	v_mfma_f32_16x16x32_bf16 v[66:69], v[222:225], v[206:209], v[66:69]
	v_mfma_f32_16x16x32_bf16 v[130:133], v[218:221], v[150:153], v[130:133]
	v_mfma_f32_16x16x32_bf16 v[114:117], v[226:229], v[150:153], v[114:117]
	v_mfma_f32_16x16x32_bf16 v[106:109], v[218:221], v[158:161], v[106:109]
	v_mfma_f32_16x16x32_bf16 v[98:101], v[226:229], v[158:161], v[98:101]
	v_mfma_f32_16x16x32_bf16 v[90:93], v[218:221], v[202:205], v[90:93]
	v_mfma_f32_16x16x32_bf16 v[82:85], v[226:229], v[202:205], v[82:85]
	v_mfma_f32_16x16x32_bf16 v[74:77], v[218:221], v[210:213], v[74:77]
	v_mfma_f32_16x16x32_bf16 v[66:69], v[226:229], v[210:213], v[66:69]
	s_mov_b32 m0, s31
	s_barrier
	ds_read_b128 v[146:149], v183 offset:16384
	ds_read_b128 v[150:153], v183 offset:17408
	ds_read_b128 v[154:157], v183 offset:18432
	ds_read_b128 v[158:161], v183 offset:19456
	ds_read_b128 v[176:179], v183 offset:20480
	ds_read_b128 v[202:205], v183 offset:21504
	ds_read_b128 v[206:209], v183 offset:22528
	ds_read_b128 v[210:213], v183 offset:23552
	global_load_lds_dwordx4 v166, s[2:3]
	s_mov_b32 m0, s39
	s_nop 0
	global_load_lds_dwordx4 v164, s[2:3]
	s_barrier
	s_waitcnt lgkmcnt(0)
	s_waitcnt lgkmcnt(0)
	v_mfma_f32_16x16x32_bf16 v[62:65], v[122:125], v[146:149], v[62:65]
	v_mfma_f32_16x16x32_bf16 v[54:57], v[138:141], v[146:149], v[54:57]
	v_mfma_f32_16x16x32_bf16 v[46:49], v[122:125], v[154:157], v[46:49]
	v_mfma_f32_16x16x32_bf16 v[38:41], v[138:141], v[154:157], v[38:41]
	v_mfma_f32_16x16x32_bf16 v[30:33], v[122:125], v[176:179], v[30:33]
	v_mfma_f32_16x16x32_bf16 v[22:25], v[138:141], v[176:179], v[22:25]
	v_mfma_f32_16x16x32_bf16 v[14:17], v[122:125], v[206:209], v[14:17]
	v_mfma_f32_16x16x32_bf16 v[6:9], v[138:141], v[206:209], v[6:9]
	v_mfma_f32_16x16x32_bf16 v[62:65], v[126:129], v[150:153], v[62:65]
	v_mfma_f32_16x16x32_bf16 v[54:57], v[142:145], v[150:153], v[54:57]
	v_mfma_f32_16x16x32_bf16 v[46:49], v[126:129], v[158:161], v[46:49]
	v_mfma_f32_16x16x32_bf16 v[38:41], v[142:145], v[158:161], v[38:41]
	v_mfma_f32_16x16x32_bf16 v[30:33], v[126:129], v[202:205], v[30:33]
	v_mfma_f32_16x16x32_bf16 v[22:25], v[142:145], v[202:205], v[22:25]
	v_mfma_f32_16x16x32_bf16 v[14:17], v[126:129], v[210:213], v[14:17]
	v_mfma_f32_16x16x32_bf16 v[6:9], v[142:145], v[210:213], v[6:9]
	s_barrier
	s_mov_b32 m0, s40
	s_nop 0
	global_load_lds_dwordx4 v240, s[26:27]
	s_mov_b32 m0, s41
	s_nop 0
	global_load_lds_dwordx4 v241, s[26:27]
	s_waitcnt vmcnt(6)
	s_barrier
	v_mfma_f32_16x16x32_bf16 v[58:61], v[214:217], v[146:149], v[58:61]
	v_mfma_f32_16x16x32_bf16 v[50:53], v[222:225], v[146:149], v[50:53]
	v_mfma_f32_16x16x32_bf16 v[42:45], v[214:217], v[154:157], v[42:45]
	v_mfma_f32_16x16x32_bf16 v[34:37], v[222:225], v[154:157], v[34:37]
	v_mfma_f32_16x16x32_bf16 v[26:29], v[214:217], v[176:179], v[26:29]
	v_mfma_f32_16x16x32_bf16 v[18:21], v[222:225], v[176:179], v[18:21]
	v_mfma_f32_16x16x32_bf16 v[10:13], v[214:217], v[206:209], v[10:13]
	v_mfma_f32_16x16x32_bf16 v[2:5], v[222:225], v[206:209], v[2:5]
	v_mfma_f32_16x16x32_bf16 v[58:61], v[218:221], v[150:153], v[58:61]
	v_mfma_f32_16x16x32_bf16 v[50:53], v[226:229], v[150:153], v[50:53]
	v_mfma_f32_16x16x32_bf16 v[42:45], v[218:221], v[158:161], v[42:45]
	v_mfma_f32_16x16x32_bf16 v[34:37], v[226:229], v[158:161], v[34:37]
	v_mfma_f32_16x16x32_bf16 v[26:29], v[218:221], v[202:205], v[26:29]
	v_mfma_f32_16x16x32_bf16 v[18:21], v[226:229], v[202:205], v[18:21]
	v_mfma_f32_16x16x32_bf16 v[10:13], v[218:221], v[210:213], v[10:13]
	v_mfma_f32_16x16x32_bf16 v[2:5], v[226:229], v[210:213], v[2:5]
	s_barrier
	ds_read_b128 v[122:125], v193
	ds_read_b128 v[126:129], v194
	ds_read_b128 v[138:141], v195
	ds_read_b128 v[142:145], v196
	s_mov_b32 m0, s42
	ds_read_b128 v[146:149], v183 offset:32768
	ds_read_b128 v[150:153], v183 offset:33792
	ds_read_b128 v[154:157], v183 offset:34816
	ds_read_b128 v[158:161], v183 offset:35840
	ds_read_b128 v[176:179], v183 offset:36864
	ds_read_b128 v[202:205], v183 offset:37888
	ds_read_b128 v[206:209], v183 offset:38912
	ds_read_b128 v[210:213], v183 offset:39936
	global_load_lds_dwordx4 v240, s[2:3]
	s_mov_b32 m0, s43
	s_nop 0
	global_load_lds_dwordx4 v241, s[2:3]
	s_waitcnt lgkmcnt(8)
	s_barrier
	s_waitcnt lgkmcnt(0)
	s_waitcnt lgkmcnt(0)
	v_mfma_f32_16x16x32_bf16 v[134:137], v[122:125], v[146:149], v[134:137]
	v_mfma_f32_16x16x32_bf16 v[118:121], v[138:141], v[146:149], v[118:121]
	v_mfma_f32_16x16x32_bf16 v[110:113], v[122:125], v[154:157], v[110:113]
	v_mfma_f32_16x16x32_bf16 v[102:105], v[138:141], v[154:157], v[102:105]
	v_mfma_f32_16x16x32_bf16 v[94:97], v[122:125], v[176:179], v[94:97]
	v_mfma_f32_16x16x32_bf16 v[86:89], v[138:141], v[176:179], v[86:89]
	v_mfma_f32_16x16x32_bf16 v[78:81], v[122:125], v[206:209], v[78:81]
	v_mfma_f32_16x16x32_bf16 v[70:73], v[138:141], v[206:209], v[70:73]
	v_mfma_f32_16x16x32_bf16 v[134:137], v[126:129], v[150:153], v[134:137]
	v_mfma_f32_16x16x32_bf16 v[118:121], v[142:145], v[150:153], v[118:121]
	v_mfma_f32_16x16x32_bf16 v[110:113], v[126:129], v[158:161], v[110:113]
	v_mfma_f32_16x16x32_bf16 v[102:105], v[142:145], v[158:161], v[102:105]
	v_mfma_f32_16x16x32_bf16 v[94:97], v[126:129], v[202:205], v[94:97]
	v_mfma_f32_16x16x32_bf16 v[86:89], v[142:145], v[202:205], v[86:89]
	v_mfma_f32_16x16x32_bf16 v[78:81], v[126:129], v[210:213], v[78:81]
	v_mfma_f32_16x16x32_bf16 v[70:73], v[142:145], v[210:213], v[70:73]
	s_barrier
	s_sub_u32 m0, s48, 0x80
	ds_read_b128 v[214:217], v197
	ds_read_b128 v[218:221], v198
	ds_read_b128 v[222:225], v199
	ds_read_b128 v[226:229], v200
	global_load_lds_dwordx4 v166, s[26:27] offset:128
	s_sub_u32 m0, s49, 0x80
	s_nop 0
	global_load_lds_dwordx4 v164, s[26:27] offset:128
	s_barrier
	s_waitcnt lgkmcnt(0)
	s_waitcnt lgkmcnt(0)
	v_mfma_f32_16x16x32_bf16 v[130:133], v[214:217], v[146:149], v[130:133]
	v_mfma_f32_16x16x32_bf16 v[114:117], v[222:225], v[146:149], v[114:117]
	v_mfma_f32_16x16x32_bf16 v[106:109], v[214:217], v[154:157], v[106:109]
	v_mfma_f32_16x16x32_bf16 v[98:101], v[222:225], v[154:157], v[98:101]
	v_mfma_f32_16x16x32_bf16 v[90:93], v[214:217], v[176:179], v[90:93]
	v_mfma_f32_16x16x32_bf16 v[82:85], v[222:225], v[176:179], v[82:85]
	v_mfma_f32_16x16x32_bf16 v[74:77], v[214:217], v[206:209], v[74:77]
	v_mfma_f32_16x16x32_bf16 v[66:69], v[222:225], v[206:209], v[66:69]
	v_mfma_f32_16x16x32_bf16 v[130:133], v[218:221], v[150:153], v[130:133]
	v_mfma_f32_16x16x32_bf16 v[114:117], v[226:229], v[150:153], v[114:117]
	v_mfma_f32_16x16x32_bf16 v[106:109], v[218:221], v[158:161], v[106:109]
	v_mfma_f32_16x16x32_bf16 v[98:101], v[226:229], v[158:161], v[98:101]
	v_mfma_f32_16x16x32_bf16 v[90:93], v[218:221], v[202:205], v[90:93]
	v_mfma_f32_16x16x32_bf16 v[82:85], v[226:229], v[202:205], v[82:85]
	v_mfma_f32_16x16x32_bf16 v[74:77], v[218:221], v[210:213], v[74:77]
	v_mfma_f32_16x16x32_bf16 v[66:69], v[226:229], v[210:213], v[66:69]
	s_sub_u32 m0, s50, 0x80
	s_barrier
	ds_read_b128 v[146:149], v183 offset:49152
	ds_read_b128 v[150:153], v183 offset:50176
	ds_read_b128 v[154:157], v183 offset:51200
	ds_read_b128 v[158:161], v183 offset:52224
	ds_read_b128 v[176:179], v183 offset:53248
	ds_read_b128 v[202:205], v183 offset:54272
	ds_read_b128 v[206:209], v183 offset:55296
	ds_read_b128 v[210:213], v183 offset:56320
	global_load_lds_dwordx4 v166, s[2:3] offset:128
	s_sub_u32 m0, s51, 0x80
	s_nop 0
	global_load_lds_dwordx4 v164, s[2:3] offset:128
	s_barrier
	s_waitcnt lgkmcnt(0)
	s_waitcnt lgkmcnt(0)
	v_mfma_f32_16x16x32_bf16 v[62:65], v[122:125], v[146:149], v[62:65]
	v_mfma_f32_16x16x32_bf16 v[54:57], v[138:141], v[146:149], v[54:57]
	v_mfma_f32_16x16x32_bf16 v[46:49], v[122:125], v[154:157], v[46:49]
	v_mfma_f32_16x16x32_bf16 v[38:41], v[138:141], v[154:157], v[38:41]
	v_mfma_f32_16x16x32_bf16 v[30:33], v[122:125], v[176:179], v[30:33]
	v_mfma_f32_16x16x32_bf16 v[22:25], v[138:141], v[176:179], v[22:25]
	v_mfma_f32_16x16x32_bf16 v[14:17], v[122:125], v[206:209], v[14:17]
	v_mfma_f32_16x16x32_bf16 v[6:9], v[138:141], v[206:209], v[6:9]
	v_mfma_f32_16x16x32_bf16 v[62:65], v[126:129], v[150:153], v[62:65]
	v_mfma_f32_16x16x32_bf16 v[54:57], v[142:145], v[150:153], v[54:57]
	v_mfma_f32_16x16x32_bf16 v[46:49], v[126:129], v[158:161], v[46:49]
	v_mfma_f32_16x16x32_bf16 v[38:41], v[142:145], v[158:161], v[38:41]
	v_mfma_f32_16x16x32_bf16 v[30:33], v[126:129], v[202:205], v[30:33]
	v_mfma_f32_16x16x32_bf16 v[22:25], v[142:145], v[202:205], v[22:25]
	v_mfma_f32_16x16x32_bf16 v[14:17], v[126:129], v[210:213], v[14:17]
	v_mfma_f32_16x16x32_bf16 v[6:9], v[142:145], v[210:213], v[6:9]
	s_barrier
	s_sub_u32 m0, s53, 0x80
	s_nop 0
	global_load_lds_dwordx4 v240, s[26:27] offset:128
	s_sub_u32 m0, s56, 0x80
	s_nop 0
	global_load_lds_dwordx4 v241, s[26:27] offset:128
	s_waitcnt vmcnt(6)
	s_barrier
	v_mfma_f32_16x16x32_bf16 v[58:61], v[214:217], v[146:149], v[58:61]
	v_mfma_f32_16x16x32_bf16 v[50:53], v[222:225], v[146:149], v[50:53]
	v_mfma_f32_16x16x32_bf16 v[42:45], v[214:217], v[154:157], v[42:45]
	v_mfma_f32_16x16x32_bf16 v[34:37], v[222:225], v[154:157], v[34:37]
	v_mfma_f32_16x16x32_bf16 v[26:29], v[214:217], v[176:179], v[26:29]
	v_mfma_f32_16x16x32_bf16 v[18:21], v[222:225], v[176:179], v[18:21]
	v_mfma_f32_16x16x32_bf16 v[10:13], v[214:217], v[206:209], v[10:13]
	v_mfma_f32_16x16x32_bf16 v[2:5], v[222:225], v[206:209], v[2:5]
	v_mfma_f32_16x16x32_bf16 v[58:61], v[218:221], v[150:153], v[58:61]
	v_mfma_f32_16x16x32_bf16 v[50:53], v[226:229], v[150:153], v[50:53]
	v_mfma_f32_16x16x32_bf16 v[42:45], v[218:221], v[158:161], v[42:45]
	v_mfma_f32_16x16x32_bf16 v[34:37], v[226:229], v[158:161], v[34:37]
	v_mfma_f32_16x16x32_bf16 v[26:29], v[218:221], v[202:205], v[26:29]
	v_mfma_f32_16x16x32_bf16 v[18:21], v[226:229], v[202:205], v[18:21]
	v_mfma_f32_16x16x32_bf16 v[10:13], v[218:221], v[210:213], v[10:13]
	v_mfma_f32_16x16x32_bf16 v[2:5], v[226:229], v[210:213], v[2:5]
	s_add_u32 s0, s0, 0x100
	s_addc_u32 s1, s1, 0
	s_add_u32 s28, s28, 0x100
	s_addc_u32 s29, s29, 0
	s_cmp_ge_i32 s36, s57
	s_mov_b32 s2, s36
	s_barrier
	s_cbranch_scc0 .LBB0_1104
	s_branch .LBB0_1095
